# static priority split, opposite half: priority 3 only from the early barrier to the loop end (MFMA + LDS-write + prefetch half); the LDS-read half runs at priority 0
# speedup vs baseline: 1.0076x; 1.0076x over previous
; __device__ __forceinline__ void lds_barrier() { asm volatile("s_waitcnt lgkmcnt(0)\n\ts_barrier" ::: "memory"); }
; __device__ __forceinline__ f32x16 mfma32(bf16x8 a, bf16x8 b, f32x16 c) { return __builtin_amdgcn_mfma_f32_32x32x16_bf16(a, b, c, 0, 0, 0); }
; __device__ __forceinline__ void gemm_big(const bf16_t* __restrict__ A, long lda, const bf16_t* __restrict__ Bt, int K, f32x16 (&acc)[2][4], unsigned char* lds) {
;     ...
;     for (int kc = 0; kc < nk; ++kc) {
;         bf16x8 af[2][2], bfr[2][4];
;         af[0][0] = *(const bf16x8*)(Ac); af[0][1] = *(const bf16x8*)(Ac + 32 * GLD);
; #pragma unroll
;         for (int ni = 0; ni < 4; ++ni) bfr[0][ni] = *(const bf16x8*)(Bc + ni * 32 * GLD);
;         __builtin_amdgcn_s_setprio(3);
; #pragma unroll
;         for (int ks = 0; ks < 4; ++ks) {
;             const int cb = ks & 1, nb = cb ^ 1;
;             if (ks < 3) {
;                 af[nb][0] = *(const bf16x8*)(Ac + (ks + 1) * 16); af[nb][1] = *(const bf16x8*)(Ac + 32 * GLD + (ks + 1) * 16);
; #pragma unroll
;                 for (int ni = 0; ni < 4; ++ni) bfr[nb][ni] = *(const bf16x8*)(Bc + ni * 32 * GLD + (ks + 1) * 16);
;             }
;             __builtin_amdgcn_sched_barrier(0);
; #pragma unroll
;             for (int ni = 0; ni < 4; ++ni) { acc[0][ni] = mfma32(af[cb][0], bfr[cb][ni], acc[0][ni]); acc[1][ni] = mfma32(af[cb][1], bfr[cb][ni], acc[1][ni]); }
;             __builtin_amdgcn_sched_barrier(0);
;         }
;         __builtin_amdgcn_s_setprio(0);
;         lds_barrier();
;         if (kc + 1 < nk) {
;             lstore();
;             if (kc + 2 < nk) gload(kc + 2);
;             lds_barrier();
;         }
;     }
; __device__ __forceinline__ void phase_resid(const Params& p, const bf16_t* A, long lda, int mrows, const bf16_t* Bt, int K, float* xres, float scale, unsigned char* lds) {
;     ...
;         gemm_big(A + (size_t)pm * 128 * lda, lda, Bt + (size_t)pn * 256 * K, K, acc, lds);
.LBB0_56:
	s_cmp_gt_u32 s13, 42
	s_cbranch_scc1 .Lmy_gorig_8
	ds_read_b128 v[190:193], v187
	ds_read_b128 v[194:197], v187 offset:4608
	ds_read_b128 v[198:201], v188 offset:18432
	ds_read_b128 v[202:205], v188 offset:23040
	ds_read_b128 v[206:209], v188 offset:27648
	ds_read_b128 v[210:213], v188 offset:32256
	ds_read_b128 v[214:217], v187 offset:32
	ds_read_b128 v[218:221], v187 offset:4640
	ds_read_b128 v[224:227], v188 offset:18464
	ds_read_b128 v[234:237], v188 offset:23072
	ds_read_b128 v[238:241], v188 offset:27680
	ds_read_b128 v[242:245], v188 offset:32288
	s_waitcnt lgkmcnt(9)
	v_mfma_f32_32x32x16_bf16 v[114:129], v[190:193], v[198:201], v[114:129]
	v_mfma_f32_32x32x16_bf16 v[50:65], v[194:197], v[198:201], v[50:65]
	s_waitcnt lgkmcnt(8)
	v_mfma_f32_32x32x16_bf16 v[98:113], v[190:193], v[202:205], v[98:113]
	v_mfma_f32_32x32x16_bf16 v[34:49], v[194:197], v[202:205], v[34:49]
	s_waitcnt lgkmcnt(7)
	v_mfma_f32_32x32x16_bf16 v[82:97], v[190:193], v[206:209], v[82:97]
	v_mfma_f32_32x32x16_bf16 v[18:33], v[194:197], v[206:209], v[18:33]
	s_waitcnt lgkmcnt(6)
	v_mfma_f32_32x32x16_bf16 v[66:81], v[190:193], v[210:213], v[66:81]
	v_mfma_f32_32x32x16_bf16 v[2:17], v[194:197], v[210:213], v[2:17]
	ds_read_b128 v[190:193], v187 offset:64
	ds_read_b128 v[194:197], v187 offset:4672
	ds_read_b128 v[198:201], v188 offset:18496
	ds_read_b128 v[202:205], v188 offset:23104
	ds_read_b128 v[206:209], v188 offset:27712
	ds_read_b128 v[210:213], v188 offset:32320
	s_waitcnt lgkmcnt(9)
	v_mfma_f32_32x32x16_bf16 v[114:129], v[214:217], v[224:227], v[114:129]
	v_mfma_f32_32x32x16_bf16 v[50:65], v[218:221], v[224:227], v[50:65]
	s_waitcnt lgkmcnt(8)
	v_mfma_f32_32x32x16_bf16 v[98:113], v[214:217], v[234:237], v[98:113]
	v_mfma_f32_32x32x16_bf16 v[34:49], v[218:221], v[234:237], v[34:49]
	s_waitcnt lgkmcnt(7)
	v_mfma_f32_32x32x16_bf16 v[82:97], v[214:217], v[238:241], v[82:97]
	v_mfma_f32_32x32x16_bf16 v[18:33], v[218:221], v[238:241], v[18:33]
	s_waitcnt lgkmcnt(6)
	v_mfma_f32_32x32x16_bf16 v[66:81], v[214:217], v[242:245], v[66:81]
	v_mfma_f32_32x32x16_bf16 v[2:17], v[218:221], v[242:245], v[2:17]
	ds_read_b128 v[214:217], v187 offset:96
	ds_read_b128 v[218:221], v187 offset:4704
	ds_read_b128 v[224:227], v188 offset:18528
	ds_read_b128 v[234:237], v188 offset:23136
	ds_read_b128 v[238:241], v188 offset:27744
	ds_read_b128 v[242:245], v188 offset:32352
	s_waitcnt lgkmcnt(9)
	v_mfma_f32_32x32x16_bf16 v[114:129], v[190:193], v[198:201], v[114:129]
	v_mfma_f32_32x32x16_bf16 v[50:65], v[194:197], v[198:201], v[50:65]
	s_waitcnt lgkmcnt(0)
	s_barrier
	s_setprio 3
	s_cmpk_eq_i32 s4, 0x1500
	s_cbranch_scc1 .Lmy_gB_8
	v_mfma_f32_32x32x16_bf16 v[98:113], v[190:193], v[202:205], v[98:113]
	s_waitcnt vmcnt(9)
	ds_write_b128 v189, v[130:133]
	v_mfma_f32_32x32x16_bf16 v[34:49], v[194:197], v[202:205], v[34:49]
	ds_write_b128 v189, v[134:137] offset:4608
	v_mfma_f32_32x32x16_bf16 v[82:97], v[190:193], v[206:209], v[82:97]
	ds_write_b128 v189, v[138:141] offset:9216
	s_add_u32 vcc_lo, s4, 0x78a8000
	s_addc_u32 vcc_hi, s5, 0
	s_nop 0
	v_lshl_add_u64 v[130:131], v[184:185], 0, vcc
	global_load_dwordx4 v[130:133], v[130:131], off offset:256
	v_mfma_f32_32x32x16_bf16 v[18:33], v[194:197], v[206:209], v[18:33]
	s_waitcnt vmcnt(8)
	ds_write_b128 v189, v[142:145] offset:13824
	s_add_u32 vcc_lo, s4, 0x78d4000
	s_addc_u32 vcc_hi, s5, 0
	s_nop 0
	v_lshl_add_u64 v[134:135], v[184:185], 0, vcc
	global_load_dwordx4 v[134:137], v[134:135], off offset:256
	v_mfma_f32_32x32x16_bf16 v[66:81], v[190:193], v[210:213], v[66:81]
	ds_write_b128 v189, v[146:149] offset:18432
	s_add_u32 vcc_lo, s4, 0x7900000
	s_addc_u32 vcc_hi, s5, 0
	s_nop 0
	v_lshl_add_u64 v[138:139], v[184:185], 0, vcc
	global_load_dwordx4 v[138:141], v[138:139], off offset:256
	v_mfma_f32_32x32x16_bf16 v[2:17], v[194:197], v[210:213], v[2:17]
	s_waitcnt vmcnt(9)
	ds_write_b128 v189, v[150:153] offset:23040
	s_add_u32 vcc_lo, s4, 0x792c000
	s_addc_u32 vcc_hi, s5, 0
	s_nop 0
	v_lshl_add_u64 v[142:143], v[184:185], 0, vcc
	global_load_dwordx4 v[142:145], v[142:143], off offset:256
	v_mfma_f32_32x32x16_bf16 v[114:129], v[214:217], v[224:227], v[114:129]
	s_waitcnt vmcnt(9)
	ds_write_b128 v189, v[154:157] offset:27648
	s_add_u32 vcc_lo, s4, 0x3328000
	s_addc_u32 vcc_hi, s5, 0
	s_nop 0
	v_lshl_add_u64 v[146:147], v[182:183], 0, vcc
	global_load_dwordx4 v[146:149], v[146:147], off offset:256
	v_mfma_f32_32x32x16_bf16 v[50:65], v[218:221], v[224:227], v[50:65]
	s_waitcnt vmcnt(9)
	ds_write_b128 v189, v[158:161] offset:32256
	s_add_u32 vcc_lo, s4, 0x3354000
	s_addc_u32 vcc_hi, s5, 0
	s_nop 0
	v_lshl_add_u64 v[150:151], v[182:183], 0, vcc
	global_load_dwordx4 v[150:153], v[150:151], off offset:256
	v_mfma_f32_32x32x16_bf16 v[98:113], v[214:217], v[234:237], v[98:113]
	s_waitcnt vmcnt(9)
	ds_write_b128 v189, v[162:165] offset:36864
	s_add_u32 vcc_lo, s4, 0x3380000
	s_addc_u32 vcc_hi, s5, 0
	s_nop 0
	v_lshl_add_u64 v[154:155], v[182:183], 0, vcc
	global_load_dwordx4 v[154:157], v[154:155], off offset:256
	v_mfma_f32_32x32x16_bf16 v[34:49], v[218:221], v[234:237], v[34:49]
	s_waitcnt vmcnt(9)
	ds_write_b128 v189, v[166:169] offset:41472
	s_add_u32 vcc_lo, s4, 0x33ac000
	s_addc_u32 vcc_hi, s5, 0
	s_nop 0
	v_lshl_add_u64 v[158:159], v[182:183], 0, vcc
	global_load_dwordx4 v[158:161], v[158:159], off offset:256
	v_mfma_f32_32x32x16_bf16 v[82:97], v[214:217], v[238:241], v[82:97]
	s_waitcnt vmcnt(9)
	ds_write_b128 v189, v[170:173] offset:46080
	s_add_u32 vcc_lo, s4, 0x33d8000
	s_addc_u32 vcc_hi, s5, 0
	s_nop 0
	v_lshl_add_u64 v[162:163], v[182:183], 0, vcc
	global_load_dwordx4 v[162:165], v[162:163], off offset:256
	v_mfma_f32_32x32x16_bf16 v[18:33], v[218:221], v[238:241], v[18:33]
	s_waitcnt vmcnt(9)
	ds_write_b128 v189, v[174:177] offset:50688
	s_add_u32 vcc_lo, s4, 0x3404000
	s_addc_u32 vcc_hi, s5, 0
	s_nop 0
	v_lshl_add_u64 v[166:167], v[182:183], 0, vcc
	global_load_dwordx4 v[166:169], v[166:167], off offset:256
	v_mfma_f32_32x32x16_bf16 v[66:81], v[214:217], v[242:245], v[66:81]
	s_add_u32 vcc_lo, s4, 0x3430000
	s_addc_u32 vcc_hi, s5, 0
	s_nop 0
	v_lshl_add_u64 v[170:171], v[182:183], 0, vcc
	global_load_dwordx4 v[170:173], v[170:171], off offset:256
	v_mfma_f32_32x32x16_bf16 v[2:17], v[218:221], v[242:245], v[2:17]
	s_add_u32 vcc_lo, s4, 0x345c000
	s_addc_u32 vcc_hi, s5, 0
	s_nop 0
	v_lshl_add_u64 v[174:175], v[182:183], 0, vcc
	global_load_dwordx4 v[174:177], v[174:175], off offset:256
	s_setprio 0
	s_branch .LBB0_54

; __device__ __forceinline__ void lds_barrier() { asm volatile("s_waitcnt lgkmcnt(0)\n\ts_barrier" ::: "memory"); }
; __device__ __forceinline__ f32x16 mfma32(bf16x8 a, bf16x8 b, f32x16 c) { return __builtin_amdgcn_mfma_f32_32x32x16_bf16(a, b, c, 0, 0, 0); }
; __device__ __forceinline__ void gemm_big(const bf16_t* __restrict__ A, long lda, const bf16_t* __restrict__ Bt, int K, f32x16 (&acc)[2][4], unsigned char* lds) {
;     ...
;     for (int kc = 0; kc < nk; ++kc) {
;         bf16x8 af[2][2], bfr[2][4];
;         af[0][0] = *(const bf16x8*)(Ac); af[0][1] = *(const bf16x8*)(Ac + 32 * GLD);
; #pragma unroll
;         for (int ni = 0; ni < 4; ++ni) bfr[0][ni] = *(const bf16x8*)(Bc + ni * 32 * GLD);
;         __builtin_amdgcn_s_setprio(3);
; #pragma unroll
;         for (int ks = 0; ks < 4; ++ks) {
;             const int cb = ks & 1, nb = cb ^ 1;
;             if (ks < 3) {
;                 af[nb][0] = *(const bf16x8*)(Ac + (ks + 1) * 16); af[nb][1] = *(const bf16x8*)(Ac + 32 * GLD + (ks + 1) * 16);
; #pragma unroll
;                 for (int ni = 0; ni < 4; ++ni) bfr[nb][ni] = *(const bf16x8*)(Bc + ni * 32 * GLD + (ks + 1) * 16);
;             }
;             __builtin_amdgcn_sched_barrier(0);
; #pragma unroll
;             for (int ni = 0; ni < 4; ++ni) { acc[0][ni] = mfma32(af[cb][0], bfr[cb][ni], acc[0][ni]); acc[1][ni] = mfma32(af[cb][1], bfr[cb][ni], acc[1][ni]); }
;             __builtin_amdgcn_sched_barrier(0);
;         }
;         __builtin_amdgcn_s_setprio(0);
;         lds_barrier();
;         if (kc + 1 < nk) {
;             lstore();
;             if (kc + 2 < nk) gload(kc + 2);
;             lds_barrier();
;         }
;     }
.LBB0_67:
	s_cmp_gt_u32 s5, 14
	s_cbranch_scc1 .Lmy_gorig_7
	ds_read_b128 v[190:193], v187
	ds_read_b128 v[194:197], v187 offset:4608
	ds_read_b128 v[198:201], v188 offset:18432
	ds_read_b128 v[202:205], v188 offset:23040
	ds_read_b128 v[206:209], v188 offset:27648
	ds_read_b128 v[210:213], v188 offset:32256
	ds_read_b128 v[214:217], v187 offset:32
	ds_read_b128 v[218:221], v187 offset:4640
	ds_read_b128 v[224:227], v188 offset:18464
	ds_read_b128 v[234:237], v188 offset:23072
	ds_read_b128 v[238:241], v188 offset:27680
	ds_read_b128 v[242:245], v188 offset:32288
	s_waitcnt lgkmcnt(9)
	v_mfma_f32_32x32x16_bf16 v[114:129], v[190:193], v[198:201], v[114:129]
	v_mfma_f32_32x32x16_bf16 v[82:97], v[194:197], v[198:201], v[82:97]
	s_waitcnt lgkmcnt(8)
	v_mfma_f32_32x32x16_bf16 v[98:113], v[190:193], v[202:205], v[98:113]
	v_mfma_f32_32x32x16_bf16 v[66:81], v[194:197], v[202:205], v[66:81]
	s_waitcnt lgkmcnt(7)
	v_mfma_f32_32x32x16_bf16 v[50:65], v[190:193], v[206:209], v[50:65]
	v_mfma_f32_32x32x16_bf16 v[18:33], v[194:197], v[206:209], v[18:33]
	s_waitcnt lgkmcnt(6)
	v_mfma_f32_32x32x16_bf16 v[34:49], v[190:193], v[210:213], v[34:49]
	v_mfma_f32_32x32x16_bf16 v[2:17], v[194:197], v[210:213], v[2:17]
	ds_read_b128 v[190:193], v187 offset:64
	ds_read_b128 v[194:197], v187 offset:4672
	ds_read_b128 v[198:201], v188 offset:18496
	ds_read_b128 v[202:205], v188 offset:23104
	ds_read_b128 v[206:209], v188 offset:27712
	ds_read_b128 v[210:213], v188 offset:32320
	s_waitcnt lgkmcnt(9)
	v_mfma_f32_32x32x16_bf16 v[114:129], v[214:217], v[224:227], v[114:129]
	v_mfma_f32_32x32x16_bf16 v[82:97], v[218:221], v[224:227], v[82:97]
	s_waitcnt lgkmcnt(8)
	v_mfma_f32_32x32x16_bf16 v[98:113], v[214:217], v[234:237], v[98:113]
	v_mfma_f32_32x32x16_bf16 v[66:81], v[218:221], v[234:237], v[66:81]
	s_waitcnt lgkmcnt(7)
	v_mfma_f32_32x32x16_bf16 v[50:65], v[214:217], v[238:241], v[50:65]
	v_mfma_f32_32x32x16_bf16 v[18:33], v[218:221], v[238:241], v[18:33]
	s_waitcnt lgkmcnt(6)
	v_mfma_f32_32x32x16_bf16 v[34:49], v[214:217], v[242:245], v[34:49]
	v_mfma_f32_32x32x16_bf16 v[2:17], v[218:221], v[242:245], v[2:17]
	ds_read_b128 v[214:217], v187 offset:96
	ds_read_b128 v[218:221], v187 offset:4704
	ds_read_b128 v[224:227], v188 offset:18528
	ds_read_b128 v[234:237], v188 offset:23136
	ds_read_b128 v[238:241], v188 offset:27744
	ds_read_b128 v[242:245], v188 offset:32352
	s_waitcnt lgkmcnt(9)
	v_mfma_f32_32x32x16_bf16 v[114:129], v[190:193], v[198:201], v[114:129]
	v_mfma_f32_32x32x16_bf16 v[82:97], v[194:197], v[198:201], v[82:97]
	s_waitcnt lgkmcnt(0)
	s_barrier
	s_setprio 3
	s_cmpk_eq_i32 s6, 0x700
	s_cbranch_scc1 .Lmy_gB_7
	v_mfma_f32_32x32x16_bf16 v[98:113], v[190:193], v[202:205], v[98:113]
	s_waitcnt vmcnt(9)
	ds_write_b128 v189, v[130:133]
	v_mfma_f32_32x32x16_bf16 v[66:81], v[194:197], v[202:205], v[66:81]
	ds_write_b128 v189, v[134:137] offset:4608
	v_mfma_f32_32x32x16_bf16 v[50:65], v[190:193], v[206:209], v[50:65]
	ds_write_b128 v189, v[138:141] offset:9216
	s_add_u32 vcc_lo, s6, 0x38a8000
	s_addc_u32 vcc_hi, s7, 0
	s_nop 0
	v_lshl_add_u64 v[130:131], v[184:185], 0, vcc
	global_load_dwordx4 v[130:133], v[130:131], off offset:256
	v_mfma_f32_32x32x16_bf16 v[18:33], v[194:197], v[206:209], v[18:33]
	s_waitcnt vmcnt(8)
	ds_write_b128 v189, v[142:145] offset:13824
	s_add_u32 vcc_lo, s6, 0x38b8000
	s_addc_u32 vcc_hi, s7, 0
	s_nop 0
	v_lshl_add_u64 v[134:135], v[184:185], 0, vcc
	global_load_dwordx4 v[134:137], v[134:135], off offset:256
	v_mfma_f32_32x32x16_bf16 v[34:49], v[190:193], v[210:213], v[34:49]
	ds_write_b128 v189, v[146:149] offset:18432
	s_add_u32 vcc_lo, s6, 0x38c8000
	s_addc_u32 vcc_hi, s7, 0
	s_nop 0
	v_lshl_add_u64 v[138:139], v[184:185], 0, vcc
	global_load_dwordx4 v[138:141], v[138:139], off offset:256
	v_mfma_f32_32x32x16_bf16 v[2:17], v[194:197], v[210:213], v[2:17]
	s_waitcnt vmcnt(9)
	ds_write_b128 v189, v[150:153] offset:23040
	s_add_u32 vcc_lo, s6, 0x38d8000
	s_addc_u32 vcc_hi, s7, 0
	s_nop 0
	v_lshl_add_u64 v[142:143], v[184:185], 0, vcc
	global_load_dwordx4 v[142:145], v[142:143], off offset:256
	v_mfma_f32_32x32x16_bf16 v[114:129], v[214:217], v[224:227], v[114:129]
	s_waitcnt vmcnt(9)
	ds_write_b128 v189, v[154:157] offset:27648
	s_add_u32 vcc_lo, s6, 0x2828000
	s_addc_u32 vcc_hi, s7, 0
	s_nop 0
	v_lshl_add_u64 v[146:147], v[182:183], 0, vcc
	global_load_dwordx4 v[146:149], v[146:147], off offset:256
	v_mfma_f32_32x32x16_bf16 v[82:97], v[218:221], v[224:227], v[82:97]
	s_waitcnt vmcnt(9)
	ds_write_b128 v189, v[158:161] offset:32256
	s_add_u32 vcc_lo, s6, 0x2838000
	s_addc_u32 vcc_hi, s7, 0
	s_nop 0
	v_lshl_add_u64 v[150:151], v[182:183], 0, vcc
	global_load_dwordx4 v[150:153], v[150:151], off offset:256
	v_mfma_f32_32x32x16_bf16 v[98:113], v[214:217], v[234:237], v[98:113]
	s_waitcnt vmcnt(9)
	ds_write_b128 v189, v[162:165] offset:36864
	s_add_u32 vcc_lo, s6, 0x2848000
	s_addc_u32 vcc_hi, s7, 0
	s_nop 0
	v_lshl_add_u64 v[154:155], v[182:183], 0, vcc
	global_load_dwordx4 v[154:157], v[154:155], off offset:256
	v_mfma_f32_32x32x16_bf16 v[66:81], v[218:221], v[234:237], v[66:81]
	s_waitcnt vmcnt(9)
	ds_write_b128 v189, v[166:169] offset:41472
	s_add_u32 vcc_lo, s6, 0x2858000
	s_addc_u32 vcc_hi, s7, 0
	s_nop 0
	v_lshl_add_u64 v[158:159], v[182:183], 0, vcc
	global_load_dwordx4 v[158:161], v[158:159], off offset:256
	v_mfma_f32_32x32x16_bf16 v[50:65], v[214:217], v[238:241], v[50:65]
	s_waitcnt vmcnt(9)
	ds_write_b128 v189, v[170:173] offset:46080
	s_add_u32 vcc_lo, s6, 0x2868000
	s_addc_u32 vcc_hi, s7, 0
	s_nop 0
	v_lshl_add_u64 v[162:163], v[182:183], 0, vcc
	global_load_dwordx4 v[162:165], v[162:163], off offset:256
	v_mfma_f32_32x32x16_bf16 v[18:33], v[218:221], v[238:241], v[18:33]
	s_waitcnt vmcnt(9)
	ds_write_b128 v189, v[174:177] offset:50688
	s_add_u32 vcc_lo, s6, 0x2878000
	s_addc_u32 vcc_hi, s7, 0
	s_nop 0
	v_lshl_add_u64 v[166:167], v[182:183], 0, vcc
	global_load_dwordx4 v[166:169], v[166:167], off offset:256
	v_mfma_f32_32x32x16_bf16 v[34:49], v[214:217], v[242:245], v[34:49]
	s_add_u32 vcc_lo, s6, 0x2888000
	s_addc_u32 vcc_hi, s7, 0
	s_nop 0
	v_lshl_add_u64 v[170:171], v[182:183], 0, vcc
	global_load_dwordx4 v[170:173], v[170:171], off offset:256
	v_mfma_f32_32x32x16_bf16 v[2:17], v[218:221], v[242:245], v[2:17]
	s_add_u32 vcc_lo, s6, 0x2898000
	s_addc_u32 vcc_hi, s7, 0
	s_nop 0
	v_lshl_add_u64 v[174:175], v[182:183], 0, vcc
	global_load_dwordx4 v[174:177], v[174:175], off offset:256
	s_setprio 0
	s_branch .LBB0_65

; __device__ __forceinline__ void lds_barrier() { asm volatile("s_waitcnt lgkmcnt(0)\n\ts_barrier" ::: "memory"); }
; __device__ __forceinline__ f32x16 mfma32(bf16x8 a, bf16x8 b, f32x16 c) { return __builtin_amdgcn_mfma_f32_32x32x16_bf16(a, b, c, 0, 0, 0); }
; __device__ __forceinline__ void gemm_big(const bf16_t* __restrict__ A, long lda, const bf16_t* __restrict__ Bt, int K, f32x16 (&acc)[2][4], unsigned char* lds) {
;     ...
;     for (int kc = 0; kc < nk; ++kc) {
;         bf16x8 af[2][2], bfr[2][4];
;         af[0][0] = *(const bf16x8*)(Ac); af[0][1] = *(const bf16x8*)(Ac + 32 * GLD);
; #pragma unroll
;         for (int ni = 0; ni < 4; ++ni) bfr[0][ni] = *(const bf16x8*)(Bc + ni * 32 * GLD);
;         __builtin_amdgcn_s_setprio(3);
; #pragma unroll
;         for (int ks = 0; ks < 4; ++ks) {
;             const int cb = ks & 1, nb = cb ^ 1;
;             if (ks < 3) {
;                 af[nb][0] = *(const bf16x8*)(Ac + (ks + 1) * 16); af[nb][1] = *(const bf16x8*)(Ac + 32 * GLD + (ks + 1) * 16);
; #pragma unroll
;                 for (int ni = 0; ni < 4; ++ni) bfr[nb][ni] = *(const bf16x8*)(Bc + ni * 32 * GLD + (ks + 1) * 16);
;             }
;             __builtin_amdgcn_sched_barrier(0);
; #pragma unroll
;             for (int ni = 0; ni < 4; ++ni) { acc[0][ni] = mfma32(af[cb][0], bfr[cb][ni], acc[0][ni]); acc[1][ni] = mfma32(af[cb][1], bfr[cb][ni], acc[1][ni]); }
;             __builtin_amdgcn_sched_barrier(0);
;         }
;         __builtin_amdgcn_s_setprio(0);
;         lds_barrier();
;         if (kc + 1 < nk) {
;             lstore();
;             if (kc + 2 < nk) gload(kc + 2);
;             lds_barrier();
;         }
;     }
.LBB0_84:
	s_cmp_gt_u32 s5, 14
	s_cbranch_scc1 .Lmy_gorig_6
	ds_read_b128 v[190:193], v187
	ds_read_b128 v[194:197], v187 offset:4608
	ds_read_b128 v[198:201], v188 offset:18432
	ds_read_b128 v[202:205], v188 offset:23040
	ds_read_b128 v[206:209], v188 offset:27648
	ds_read_b128 v[210:213], v188 offset:32256
	ds_read_b128 v[214:217], v187 offset:32
	ds_read_b128 v[218:221], v187 offset:4640
	ds_read_b128 v[224:227], v188 offset:18464
	ds_read_b128 v[234:237], v188 offset:23072
	ds_read_b128 v[238:241], v188 offset:27680
	ds_read_b128 v[242:245], v188 offset:32288
	s_waitcnt lgkmcnt(9)
	v_mfma_f32_32x32x16_bf16 v[114:129], v[190:193], v[198:201], v[114:129]
	v_mfma_f32_32x32x16_bf16 v[50:65], v[194:197], v[198:201], v[50:65]
	s_waitcnt lgkmcnt(8)
	v_mfma_f32_32x32x16_bf16 v[98:113], v[190:193], v[202:205], v[98:113]
	v_mfma_f32_32x32x16_bf16 v[34:49], v[194:197], v[202:205], v[34:49]
	s_waitcnt lgkmcnt(7)
	v_mfma_f32_32x32x16_bf16 v[82:97], v[190:193], v[206:209], v[82:97]
	v_mfma_f32_32x32x16_bf16 v[18:33], v[194:197], v[206:209], v[18:33]
	s_waitcnt lgkmcnt(6)
	v_mfma_f32_32x32x16_bf16 v[66:81], v[190:193], v[210:213], v[66:81]
	v_mfma_f32_32x32x16_bf16 v[2:17], v[194:197], v[210:213], v[2:17]
	ds_read_b128 v[190:193], v187 offset:64
	ds_read_b128 v[194:197], v187 offset:4672
	ds_read_b128 v[198:201], v188 offset:18496
	ds_read_b128 v[202:205], v188 offset:23104
	ds_read_b128 v[206:209], v188 offset:27712
	ds_read_b128 v[210:213], v188 offset:32320
	s_waitcnt lgkmcnt(9)
	v_mfma_f32_32x32x16_bf16 v[114:129], v[214:217], v[224:227], v[114:129]
	v_mfma_f32_32x32x16_bf16 v[50:65], v[218:221], v[224:227], v[50:65]
	s_waitcnt lgkmcnt(8)
	v_mfma_f32_32x32x16_bf16 v[98:113], v[214:217], v[234:237], v[98:113]
	v_mfma_f32_32x32x16_bf16 v[34:49], v[218:221], v[234:237], v[34:49]
	s_waitcnt lgkmcnt(7)
	v_mfma_f32_32x32x16_bf16 v[82:97], v[214:217], v[238:241], v[82:97]
	v_mfma_f32_32x32x16_bf16 v[18:33], v[218:221], v[238:241], v[18:33]
	s_waitcnt lgkmcnt(6)
	v_mfma_f32_32x32x16_bf16 v[66:81], v[214:217], v[242:245], v[66:81]
	v_mfma_f32_32x32x16_bf16 v[2:17], v[218:221], v[242:245], v[2:17]
	ds_read_b128 v[214:217], v187 offset:96
	ds_read_b128 v[218:221], v187 offset:4704
	ds_read_b128 v[224:227], v188 offset:18528
	ds_read_b128 v[234:237], v188 offset:23136
	ds_read_b128 v[238:241], v188 offset:27744
	ds_read_b128 v[242:245], v188 offset:32352
	s_waitcnt lgkmcnt(9)
	v_mfma_f32_32x32x16_bf16 v[114:129], v[190:193], v[198:201], v[114:129]
	v_mfma_f32_32x32x16_bf16 v[50:65], v[194:197], v[198:201], v[50:65]
	s_waitcnt lgkmcnt(0)
	s_barrier
	s_setprio 3
	s_cmpk_eq_i32 s6, 0x700
	s_cbranch_scc1 .Lmy_gB_6
	v_mfma_f32_32x32x16_bf16 v[98:113], v[190:193], v[202:205], v[98:113]
	s_waitcnt vmcnt(9)
	ds_write_b128 v189, v[130:133]
	v_mfma_f32_32x32x16_bf16 v[34:49], v[194:197], v[202:205], v[34:49]
	ds_write_b128 v189, v[134:137] offset:4608
	v_mfma_f32_32x32x16_bf16 v[82:97], v[190:193], v[206:209], v[82:97]
	ds_write_b128 v189, v[138:141] offset:9216
	s_add_u32 vcc_lo, s6, 0x14948000
	s_addc_u32 vcc_hi, s7, 0
	s_nop 0
	v_lshl_add_u64 v[130:131], v[184:185], 0, vcc
	global_load_dwordx4 v[130:133], v[130:131], off offset:256
	v_mfma_f32_32x32x16_bf16 v[18:33], v[194:197], v[206:209], v[18:33]
	s_waitcnt vmcnt(8)
	ds_write_b128 v189, v[142:145] offset:13824
	s_add_u32 vcc_lo, s6, 0x14958000
	s_addc_u32 vcc_hi, s7, 0
	s_nop 0
	v_lshl_add_u64 v[134:135], v[184:185], 0, vcc
	global_load_dwordx4 v[134:137], v[134:135], off offset:256
	v_mfma_f32_32x32x16_bf16 v[66:81], v[190:193], v[210:213], v[66:81]
	ds_write_b128 v189, v[146:149] offset:18432
	s_add_u32 vcc_lo, s6, 0x14968000
	s_addc_u32 vcc_hi, s7, 0
	s_nop 0
	v_lshl_add_u64 v[138:139], v[184:185], 0, vcc
	global_load_dwordx4 v[138:141], v[138:139], off offset:256
	v_mfma_f32_32x32x16_bf16 v[2:17], v[194:197], v[210:213], v[2:17]
	s_waitcnt vmcnt(9)
	ds_write_b128 v189, v[150:153] offset:23040
	s_add_u32 vcc_lo, s6, 0x14978000
	s_addc_u32 vcc_hi, s7, 0
	s_nop 0
	v_lshl_add_u64 v[142:143], v[184:185], 0, vcc
	global_load_dwordx4 v[142:145], v[142:143], off offset:256
	v_mfma_f32_32x32x16_bf16 v[114:129], v[214:217], v[224:227], v[114:129]
	s_waitcnt vmcnt(9)
	ds_write_b128 v189, v[154:157] offset:27648
	s_add_u32 vcc_lo, s6, 0x2628000
	s_addc_u32 vcc_hi, s7, 0
	s_nop 0
	v_lshl_add_u64 v[146:147], v[182:183], 0, vcc
	global_load_dwordx4 v[146:149], v[146:147], off offset:256
	v_mfma_f32_32x32x16_bf16 v[50:65], v[218:221], v[224:227], v[50:65]
	s_waitcnt vmcnt(9)
	ds_write_b128 v189, v[158:161] offset:32256
	s_add_u32 vcc_lo, s6, 0x2638000
	s_addc_u32 vcc_hi, s7, 0
	s_nop 0
	v_lshl_add_u64 v[150:151], v[182:183], 0, vcc
	global_load_dwordx4 v[150:153], v[150:151], off offset:256
	v_mfma_f32_32x32x16_bf16 v[98:113], v[214:217], v[234:237], v[98:113]
	s_waitcnt vmcnt(9)
	ds_write_b128 v189, v[162:165] offset:36864
	s_add_u32 vcc_lo, s6, 0x2648000
	s_addc_u32 vcc_hi, s7, 0
	s_nop 0
	v_lshl_add_u64 v[154:155], v[182:183], 0, vcc
	global_load_dwordx4 v[154:157], v[154:155], off offset:256
	v_mfma_f32_32x32x16_bf16 v[34:49], v[218:221], v[234:237], v[34:49]
	s_waitcnt vmcnt(9)
	ds_write_b128 v189, v[166:169] offset:41472
	s_add_u32 vcc_lo, s6, 0x2658000
	s_addc_u32 vcc_hi, s7, 0
	s_nop 0
	v_lshl_add_u64 v[158:159], v[182:183], 0, vcc
	global_load_dwordx4 v[158:161], v[158:159], off offset:256
	v_mfma_f32_32x32x16_bf16 v[82:97], v[214:217], v[238:241], v[82:97]
	s_waitcnt vmcnt(9)
	ds_write_b128 v189, v[170:173] offset:46080
	s_add_u32 vcc_lo, s6, 0x2668000
	s_addc_u32 vcc_hi, s7, 0
	s_nop 0
	v_lshl_add_u64 v[162:163], v[182:183], 0, vcc
	global_load_dwordx4 v[162:165], v[162:163], off offset:256
	v_mfma_f32_32x32x16_bf16 v[18:33], v[218:221], v[238:241], v[18:33]
	s_waitcnt vmcnt(9)
	ds_write_b128 v189, v[174:177] offset:50688
	s_add_u32 vcc_lo, s6, 0x2678000
	s_addc_u32 vcc_hi, s7, 0
	s_nop 0
	v_lshl_add_u64 v[166:167], v[182:183], 0, vcc
	global_load_dwordx4 v[166:169], v[166:167], off offset:256
	v_mfma_f32_32x32x16_bf16 v[66:81], v[214:217], v[242:245], v[66:81]
	s_add_u32 vcc_lo, s6, 0x2688000
	s_addc_u32 vcc_hi, s7, 0
	s_nop 0
	v_lshl_add_u64 v[170:171], v[182:183], 0, vcc
	global_load_dwordx4 v[170:173], v[170:171], off offset:256
	v_mfma_f32_32x32x16_bf16 v[2:17], v[218:221], v[242:245], v[2:17]
	s_add_u32 vcc_lo, s6, 0x2698000
	s_addc_u32 vcc_hi, s7, 0
	s_nop 0
	v_lshl_add_u64 v[174:175], v[182:183], 0, vcc
	global_load_dwordx4 v[174:177], v[174:175], off offset:256
	s_setprio 0
	s_branch .LBB0_82

; __device__ __forceinline__ void lds_barrier() { asm volatile("s_waitcnt lgkmcnt(0)\n\ts_barrier" ::: "memory"); }
; __device__ __forceinline__ f32x16 mfma32(bf16x8 a, bf16x8 b, f32x16 c) { return __builtin_amdgcn_mfma_f32_32x32x16_bf16(a, b, c, 0, 0, 0); }
; __device__ __forceinline__ void gemm_big(const bf16_t* __restrict__ A, long lda, const bf16_t* __restrict__ Bt, int K, f32x16 (&acc)[2][4], unsigned char* lds) {
;     ...
;     for (int kc = 0; kc < nk; ++kc) {
;         bf16x8 af[2][2], bfr[2][4];
;         af[0][0] = *(const bf16x8*)(Ac); af[0][1] = *(const bf16x8*)(Ac + 32 * GLD);
; #pragma unroll
;         for (int ni = 0; ni < 4; ++ni) bfr[0][ni] = *(const bf16x8*)(Bc + ni * 32 * GLD);
;         __builtin_amdgcn_s_setprio(3);
; #pragma unroll
;         for (int ks = 0; ks < 4; ++ks) {
;             const int cb = ks & 1, nb = cb ^ 1;
;             if (ks < 3) {
;                 af[nb][0] = *(const bf16x8*)(Ac + (ks + 1) * 16); af[nb][1] = *(const bf16x8*)(Ac + 32 * GLD + (ks + 1) * 16);
; #pragma unroll
;                 for (int ni = 0; ni < 4; ++ni) bfr[nb][ni] = *(const bf16x8*)(Bc + ni * 32 * GLD + (ks + 1) * 16);
;             }
;             __builtin_amdgcn_sched_barrier(0);
; #pragma unroll
;             for (int ni = 0; ni < 4; ++ni) { acc[0][ni] = mfma32(af[cb][0], bfr[cb][ni], acc[0][ni]); acc[1][ni] = mfma32(af[cb][1], bfr[cb][ni], acc[1][ni]); }
;             __builtin_amdgcn_sched_barrier(0);
;         }
;         __builtin_amdgcn_s_setprio(0);
;         lds_barrier();
;         if (kc + 1 < nk) {
;             lstore();
;             if (kc + 2 < nk) gload(kc + 2);
;             lds_barrier();
;         }
;     }
.LBB0_115:
	s_cmp_gt_u32 s5, 14
	s_cbranch_scc1 .Lmy_gorig_5
	ds_read_b128 v[190:193], v187
	ds_read_b128 v[194:197], v187 offset:4608
	ds_read_b128 v[198:201], v188 offset:18432
	ds_read_b128 v[202:205], v188 offset:23040
	ds_read_b128 v[206:209], v188 offset:27648
	ds_read_b128 v[210:213], v188 offset:32256
	ds_read_b128 v[214:217], v187 offset:32
	ds_read_b128 v[218:221], v187 offset:4640
	ds_read_b128 v[224:227], v188 offset:18464
	ds_read_b128 v[234:237], v188 offset:23072
	ds_read_b128 v[238:241], v188 offset:27680
	ds_read_b128 v[242:245], v188 offset:32288
	s_waitcnt lgkmcnt(9)
	v_mfma_f32_32x32x16_bf16 v[114:129], v[190:193], v[198:201], v[114:129]
	v_mfma_f32_32x32x16_bf16 v[98:113], v[194:197], v[198:201], v[98:113]
	s_waitcnt lgkmcnt(8)
	v_mfma_f32_32x32x16_bf16 v[82:97], v[190:193], v[202:205], v[82:97]
	v_mfma_f32_32x32x16_bf16 v[66:81], v[194:197], v[202:205], v[66:81]
	s_waitcnt lgkmcnt(7)
	v_mfma_f32_32x32x16_bf16 v[50:65], v[190:193], v[206:209], v[50:65]
	v_mfma_f32_32x32x16_bf16 v[34:49], v[194:197], v[206:209], v[34:49]
	s_waitcnt lgkmcnt(6)
	v_mfma_f32_32x32x16_bf16 v[18:33], v[190:193], v[210:213], v[18:33]
	v_mfma_f32_32x32x16_bf16 v[2:17], v[194:197], v[210:213], v[2:17]
	ds_read_b128 v[190:193], v187 offset:64
	ds_read_b128 v[194:197], v187 offset:4672
	ds_read_b128 v[198:201], v188 offset:18496
	ds_read_b128 v[202:205], v188 offset:23104
	ds_read_b128 v[206:209], v188 offset:27712
	ds_read_b128 v[210:213], v188 offset:32320
	s_waitcnt lgkmcnt(9)
	v_mfma_f32_32x32x16_bf16 v[114:129], v[214:217], v[224:227], v[114:129]
	v_mfma_f32_32x32x16_bf16 v[98:113], v[218:221], v[224:227], v[98:113]
	s_waitcnt lgkmcnt(8)
	v_mfma_f32_32x32x16_bf16 v[82:97], v[214:217], v[234:237], v[82:97]
	v_mfma_f32_32x32x16_bf16 v[66:81], v[218:221], v[234:237], v[66:81]
	s_waitcnt lgkmcnt(7)
	v_mfma_f32_32x32x16_bf16 v[50:65], v[214:217], v[238:241], v[50:65]
	v_mfma_f32_32x32x16_bf16 v[34:49], v[218:221], v[238:241], v[34:49]
	s_waitcnt lgkmcnt(6)
	v_mfma_f32_32x32x16_bf16 v[18:33], v[214:217], v[242:245], v[18:33]
	v_mfma_f32_32x32x16_bf16 v[2:17], v[218:221], v[242:245], v[2:17]
	ds_read_b128 v[214:217], v187 offset:96
	ds_read_b128 v[218:221], v187 offset:4704
	ds_read_b128 v[224:227], v188 offset:18528
	ds_read_b128 v[234:237], v188 offset:23136
	ds_read_b128 v[238:241], v188 offset:27744
	ds_read_b128 v[242:245], v188 offset:32352
	s_waitcnt lgkmcnt(9)
	v_mfma_f32_32x32x16_bf16 v[114:129], v[190:193], v[198:201], v[114:129]
	v_mfma_f32_32x32x16_bf16 v[98:113], v[194:197], v[198:201], v[98:113]
	s_waitcnt lgkmcnt(0)
	s_barrier
	s_setprio 3
	s_cmpk_eq_i32 s6, 0x700
	s_cbranch_scc1 .Lmy_gB_5
	v_mfma_f32_32x32x16_bf16 v[82:97], v[190:193], v[202:205], v[82:97]
	s_waitcnt vmcnt(9)
	ds_write_b128 v189, v[130:133]
	v_mfma_f32_32x32x16_bf16 v[66:81], v[194:197], v[202:205], v[66:81]
	ds_write_b128 v189, v[134:137] offset:4608
	v_mfma_f32_32x32x16_bf16 v[50:65], v[190:193], v[206:209], v[50:65]
	ds_write_b128 v189, v[138:141] offset:9216
	s_add_u32 vcc_lo, s6, 0x38a8000
	s_addc_u32 vcc_hi, s7, 0
	s_nop 0
	v_lshl_add_u64 v[130:131], v[184:185], 0, vcc
	global_load_dwordx4 v[130:133], v[130:131], off offset:256
	v_mfma_f32_32x32x16_bf16 v[34:49], v[194:197], v[206:209], v[34:49]
	s_waitcnt vmcnt(8)
	ds_write_b128 v189, v[142:145] offset:13824
	s_add_u32 vcc_lo, s6, 0x38b8000
	s_addc_u32 vcc_hi, s7, 0
	s_nop 0
	v_lshl_add_u64 v[134:135], v[184:185], 0, vcc
	global_load_dwordx4 v[134:137], v[134:135], off offset:256
	v_mfma_f32_32x32x16_bf16 v[18:33], v[190:193], v[210:213], v[18:33]
	ds_write_b128 v189, v[146:149] offset:18432
	s_add_u32 vcc_lo, s6, 0x38c8000
	s_addc_u32 vcc_hi, s7, 0
	s_nop 0
	v_lshl_add_u64 v[138:139], v[184:185], 0, vcc
	global_load_dwordx4 v[138:141], v[138:139], off offset:256
	v_mfma_f32_32x32x16_bf16 v[2:17], v[194:197], v[210:213], v[2:17]
	s_waitcnt vmcnt(9)
	ds_write_b128 v189, v[150:153] offset:23040
	s_add_u32 vcc_lo, s6, 0x38d8000
	s_addc_u32 vcc_hi, s7, 0
	s_nop 0
	v_lshl_add_u64 v[142:143], v[184:185], 0, vcc
	global_load_dwordx4 v[142:145], v[142:143], off offset:256
	v_mfma_f32_32x32x16_bf16 v[114:129], v[214:217], v[224:227], v[114:129]
	s_waitcnt vmcnt(9)
	ds_write_b128 v189, v[154:157] offset:27648
	s_add_u32 vcc_lo, s6, 0x1c88000
	s_addc_u32 vcc_hi, s7, 0
	s_nop 0
	v_lshl_add_u64 v[146:147], v[182:183], 0, vcc
	global_load_dwordx4 v[146:149], v[146:147], off offset:256
	v_mfma_f32_32x32x16_bf16 v[98:113], v[218:221], v[224:227], v[98:113]
	s_waitcnt vmcnt(9)
	ds_write_b128 v189, v[158:161] offset:32256
	s_add_u32 vcc_lo, s6, 0x1c98000
	s_addc_u32 vcc_hi, s7, 0
	s_nop 0
	v_lshl_add_u64 v[150:151], v[182:183], 0, vcc
	global_load_dwordx4 v[150:153], v[150:151], off offset:256
	v_mfma_f32_32x32x16_bf16 v[82:97], v[214:217], v[234:237], v[82:97]
	s_waitcnt vmcnt(9)
	ds_write_b128 v189, v[162:165] offset:36864
	s_add_u32 vcc_lo, s6, 0x1ca8000
	s_addc_u32 vcc_hi, s7, 0
	s_nop 0
	v_lshl_add_u64 v[154:155], v[182:183], 0, vcc
	global_load_dwordx4 v[154:157], v[154:155], off offset:256
	v_mfma_f32_32x32x16_bf16 v[66:81], v[218:221], v[234:237], v[66:81]
	s_waitcnt vmcnt(9)
	ds_write_b128 v189, v[166:169] offset:41472
	s_add_u32 vcc_lo, s6, 0x1cb8000
	s_addc_u32 vcc_hi, s7, 0
	s_nop 0
	v_lshl_add_u64 v[158:159], v[182:183], 0, vcc
	global_load_dwordx4 v[158:161], v[158:159], off offset:256
	v_mfma_f32_32x32x16_bf16 v[50:65], v[214:217], v[238:241], v[50:65]
	s_waitcnt vmcnt(9)
	ds_write_b128 v189, v[170:173] offset:46080
	s_add_u32 vcc_lo, s6, 0x1cc8000
	s_addc_u32 vcc_hi, s7, 0
	s_nop 0
	v_lshl_add_u64 v[162:163], v[182:183], 0, vcc
	global_load_dwordx4 v[162:165], v[162:163], off offset:256
	v_mfma_f32_32x32x16_bf16 v[34:49], v[218:221], v[238:241], v[34:49]
	s_waitcnt vmcnt(9)
	ds_write_b128 v189, v[174:177] offset:50688
	s_add_u32 vcc_lo, s6, 0x1cd8000
	s_addc_u32 vcc_hi, s7, 0
	s_nop 0
	v_lshl_add_u64 v[166:167], v[182:183], 0, vcc
	global_load_dwordx4 v[166:169], v[166:167], off offset:256
	v_mfma_f32_32x32x16_bf16 v[18:33], v[214:217], v[242:245], v[18:33]
	s_add_u32 vcc_lo, s6, 0x1ce8000
	s_addc_u32 vcc_hi, s7, 0
	s_nop 0
	v_lshl_add_u64 v[170:171], v[182:183], 0, vcc
	global_load_dwordx4 v[170:173], v[170:171], off offset:256
	v_mfma_f32_32x32x16_bf16 v[2:17], v[218:221], v[242:245], v[2:17]
	s_add_u32 vcc_lo, s6, 0x1cf8000
	s_addc_u32 vcc_hi, s7, 0
	s_nop 0
	v_lshl_add_u64 v[174:175], v[182:183], 0, vcc
	global_load_dwordx4 v[174:177], v[174:175], off offset:256
	s_setprio 0
	s_branch .LBB0_113

; __device__ __forceinline__ void lds_barrier() { asm volatile("s_waitcnt lgkmcnt(0)\n\ts_barrier" ::: "memory"); }
; __device__ __forceinline__ f32x16 mfma32(bf16x8 a, bf16x8 b, f32x16 c) { return __builtin_amdgcn_mfma_f32_32x32x16_bf16(a, b, c, 0, 0, 0); }
; __device__ __forceinline__ void gemm_big(const bf16_t* __restrict__ A, long lda, const bf16_t* __restrict__ Bt, int K, f32x16 (&acc)[2][4], unsigned char* lds) {
;     ...
;     for (int kc = 0; kc < nk; ++kc) {
;         bf16x8 af[2][2], bfr[2][4];
;         af[0][0] = *(const bf16x8*)(Ac); af[0][1] = *(const bf16x8*)(Ac + 32 * GLD);
; #pragma unroll
;         for (int ni = 0; ni < 4; ++ni) bfr[0][ni] = *(const bf16x8*)(Bc + ni * 32 * GLD);
;         __builtin_amdgcn_s_setprio(3);
; #pragma unroll
;         for (int ks = 0; ks < 4; ++ks) {
;             const int cb = ks & 1, nb = cb ^ 1;
;             if (ks < 3) {
;                 af[nb][0] = *(const bf16x8*)(Ac + (ks + 1) * 16); af[nb][1] = *(const bf16x8*)(Ac + 32 * GLD + (ks + 1) * 16);
; #pragma unroll
;                 for (int ni = 0; ni < 4; ++ni) bfr[nb][ni] = *(const bf16x8*)(Bc + ni * 32 * GLD + (ks + 1) * 16);
;             }
;             __builtin_amdgcn_sched_barrier(0);
; #pragma unroll
;             for (int ni = 0; ni < 4; ++ni) { acc[0][ni] = mfma32(af[cb][0], bfr[cb][ni], acc[0][ni]); acc[1][ni] = mfma32(af[cb][1], bfr[cb][ni], acc[1][ni]); }
;             __builtin_amdgcn_sched_barrier(0);
;         }
;         __builtin_amdgcn_s_setprio(0);
;         lds_barrier();
;         if (kc + 1 < nk) {
;             lstore();
;             if (kc + 2 < nk) gload(kc + 2);
;             lds_barrier();
;         }
;     }
; __device__ __forceinline__ void mla_up_tile(const Params& p, int b, int it, unsigned char* lds) {
;     ...
;         const int pn = it % 3, pm = it / 3;
;         gemm_big(PB + (size_t)pm * 128 * PBW + PB_CQ, PBW, wb + W_UQ + (size_t)pn * 256 * 256, 256, acc, lds);
.LBB0_283:
	s_cmp_gt_u32 s5, 2
	s_cbranch_scc1 .Lmy_gorig_3
	ds_read_b128 v[192:195], v189
	ds_read_b128 v[196:199], v189 offset:4608
	ds_read_b128 v[200:203], v190 offset:18432
	ds_read_b128 v[204:207], v190 offset:23040
	ds_read_b128 v[208:211], v190 offset:27648
	ds_read_b128 v[212:215], v190 offset:32256
	ds_read_b128 v[216:219], v189 offset:32
	ds_read_b128 v[224:227], v189 offset:4640
	ds_read_b128 v[234:237], v190 offset:18464
	ds_read_b128 v[238:241], v190 offset:23072
	ds_read_b128 v[242:245], v190 offset:27680
	ds_read_b128 v[246:249], v190 offset:32288
	s_waitcnt lgkmcnt(9)
	v_mfma_f32_32x32x16_bf16 v[114:129], v[192:195], v[200:203], v[114:129]
	v_mfma_f32_32x32x16_bf16 v[50:65], v[196:199], v[200:203], v[50:65]
	s_waitcnt lgkmcnt(8)
	v_mfma_f32_32x32x16_bf16 v[98:113], v[192:195], v[204:207], v[98:113]
	v_mfma_f32_32x32x16_bf16 v[34:49], v[196:199], v[204:207], v[34:49]
	s_waitcnt lgkmcnt(7)
	v_mfma_f32_32x32x16_bf16 v[82:97], v[192:195], v[208:211], v[82:97]
	v_mfma_f32_32x32x16_bf16 v[18:33], v[196:199], v[208:211], v[18:33]
	s_waitcnt lgkmcnt(6)
	v_mfma_f32_32x32x16_bf16 v[66:81], v[192:195], v[212:215], v[66:81]
	v_mfma_f32_32x32x16_bf16 v[2:17], v[196:199], v[212:215], v[2:17]
	ds_read_b128 v[192:195], v189 offset:64
	ds_read_b128 v[196:199], v189 offset:4672
	ds_read_b128 v[200:203], v190 offset:18496
	ds_read_b128 v[204:207], v190 offset:23104
	ds_read_b128 v[208:211], v190 offset:27712
	ds_read_b128 v[212:215], v190 offset:32320
	s_waitcnt lgkmcnt(9)
	v_mfma_f32_32x32x16_bf16 v[114:129], v[216:219], v[234:237], v[114:129]
	v_mfma_f32_32x32x16_bf16 v[50:65], v[224:227], v[234:237], v[50:65]
	s_waitcnt lgkmcnt(8)
	v_mfma_f32_32x32x16_bf16 v[98:113], v[216:219], v[238:241], v[98:113]
	v_mfma_f32_32x32x16_bf16 v[34:49], v[224:227], v[238:241], v[34:49]
	s_waitcnt lgkmcnt(7)
	v_mfma_f32_32x32x16_bf16 v[82:97], v[216:219], v[242:245], v[82:97]
	v_mfma_f32_32x32x16_bf16 v[18:33], v[224:227], v[242:245], v[18:33]
	s_waitcnt lgkmcnt(6)
	v_mfma_f32_32x32x16_bf16 v[66:81], v[216:219], v[246:249], v[66:81]
	v_mfma_f32_32x32x16_bf16 v[2:17], v[224:227], v[246:249], v[2:17]
	ds_read_b128 v[216:219], v189 offset:96
	ds_read_b128 v[224:227], v189 offset:4704
	ds_read_b128 v[234:237], v190 offset:18528
	ds_read_b128 v[238:241], v190 offset:23136
	ds_read_b128 v[242:245], v190 offset:27744
	ds_read_b128 v[246:249], v190 offset:32352
	s_waitcnt lgkmcnt(9)
	v_mfma_f32_32x32x16_bf16 v[114:129], v[192:195], v[200:203], v[114:129]
	v_mfma_f32_32x32x16_bf16 v[50:65], v[196:199], v[200:203], v[50:65]
	s_waitcnt lgkmcnt(0)
	s_barrier
	s_setprio 3
	s_cmpk_eq_i32 s6, 0x100
	s_cbranch_scc1 .Lmy_gB_3
	v_mfma_f32_32x32x16_bf16 v[98:113], v[192:195], v[204:207], v[98:113]
	s_waitcnt vmcnt(9)
	ds_write_b128 v191, v[130:133]
	v_mfma_f32_32x32x16_bf16 v[34:49], v[196:199], v[204:207], v[34:49]
	ds_write_b128 v191, v[134:137] offset:4608
	v_mfma_f32_32x32x16_bf16 v[82:97], v[192:195], v[208:211], v[82:97]
	ds_write_b128 v191, v[138:141] offset:9216
	s_add_u32 vcc_lo, s6, 0x78a8000
	s_addc_u32 vcc_hi, s7, 0
	s_nop 0
	v_lshl_add_u64 v[130:131], v[184:185], 0, vcc
	global_load_dwordx4 v[130:133], v[130:131], off offset:3328
	v_mfma_f32_32x32x16_bf16 v[18:33], v[196:199], v[208:211], v[18:33]
	s_waitcnt vmcnt(8)
	ds_write_b128 v191, v[142:145] offset:13824
	s_add_u32 vcc_lo, s6, 0x78e6000
	s_addc_u32 vcc_hi, s7, 0
	s_nop 0
	v_lshl_add_u64 v[134:135], v[184:185], 0, vcc
	global_load_dwordx4 v[134:137], v[134:135], off offset:3328
	v_mfma_f32_32x32x16_bf16 v[66:81], v[192:195], v[212:215], v[66:81]
	ds_write_b128 v191, v[146:149] offset:18432
	s_add_u32 vcc_lo, s6, 0x7924000
	s_addc_u32 vcc_hi, s7, 0
	s_nop 0
	v_lshl_add_u64 v[138:139], v[184:185], 0, vcc
	global_load_dwordx4 v[138:141], v[138:139], off offset:3328
	v_mfma_f32_32x32x16_bf16 v[2:17], v[196:199], v[212:215], v[2:17]
	s_waitcnt vmcnt(9)
	ds_write_b128 v191, v[150:153] offset:23040
	s_add_u32 vcc_lo, s6, 0x7962000
	s_addc_u32 vcc_hi, s7, 0
	s_nop 0
	v_lshl_add_u64 v[142:143], v[184:185], 0, vcc
	global_load_dwordx4 v[142:145], v[142:143], off offset:3328
	v_mfma_f32_32x32x16_bf16 v[114:129], v[216:219], v[234:237], v[114:129]
	s_waitcnt vmcnt(9)
	ds_write_b128 v191, v[154:157] offset:27648
	s_add_u32 vcc_lo, s6, 0x2288000
	s_addc_u32 vcc_hi, s7, 0
	s_nop 0
	v_lshl_add_u64 v[146:147], v[182:183], 0, vcc
	global_load_dwordx4 v[146:149], v[146:147], off offset:256
	v_mfma_f32_32x32x16_bf16 v[50:65], v[224:227], v[234:237], v[50:65]
	s_waitcnt vmcnt(9)
	ds_write_b128 v191, v[158:161] offset:32256
	s_add_u32 vcc_lo, s6, 0x228c000
	s_addc_u32 vcc_hi, s7, 0
	s_nop 0
	v_lshl_add_u64 v[150:151], v[182:183], 0, vcc
	global_load_dwordx4 v[150:153], v[150:151], off offset:256
	v_mfma_f32_32x32x16_bf16 v[98:113], v[216:219], v[238:241], v[98:113]
	s_waitcnt vmcnt(9)
	ds_write_b128 v191, v[162:165] offset:36864
	s_add_u32 vcc_lo, s6, 0x2290000
	s_addc_u32 vcc_hi, s7, 0
	s_nop 0
	v_lshl_add_u64 v[154:155], v[182:183], 0, vcc
	global_load_dwordx4 v[154:157], v[154:155], off offset:256
	v_mfma_f32_32x32x16_bf16 v[34:49], v[224:227], v[238:241], v[34:49]
	s_waitcnt vmcnt(9)
	ds_write_b128 v191, v[166:169] offset:41472
	s_add_u32 vcc_lo, s6, 0x2294000
	s_addc_u32 vcc_hi, s7, 0
	s_nop 0
	v_lshl_add_u64 v[158:159], v[182:183], 0, vcc
	global_load_dwordx4 v[158:161], v[158:159], off offset:256
	v_mfma_f32_32x32x16_bf16 v[82:97], v[216:219], v[242:245], v[82:97]
	s_waitcnt vmcnt(9)
	ds_write_b128 v191, v[170:173] offset:46080
	s_add_u32 vcc_lo, s6, 0x2298000
	s_addc_u32 vcc_hi, s7, 0
	s_nop 0
	v_lshl_add_u64 v[162:163], v[182:183], 0, vcc
	global_load_dwordx4 v[162:165], v[162:163], off offset:256
	v_mfma_f32_32x32x16_bf16 v[18:33], v[224:227], v[242:245], v[18:33]
	s_waitcnt vmcnt(9)
	ds_write_b128 v191, v[174:177] offset:50688
	s_add_u32 vcc_lo, s6, 0x229c000
	s_addc_u32 vcc_hi, s7, 0
	s_nop 0
	v_lshl_add_u64 v[166:167], v[182:183], 0, vcc
	global_load_dwordx4 v[166:169], v[166:167], off offset:256
	v_mfma_f32_32x32x16_bf16 v[66:81], v[216:219], v[246:249], v[66:81]
	s_add_u32 vcc_lo, s6, 0x22a0000
	s_addc_u32 vcc_hi, s7, 0
	s_nop 0
	v_lshl_add_u64 v[170:171], v[182:183], 0, vcc
	global_load_dwordx4 v[170:173], v[170:171], off offset:256
	v_mfma_f32_32x32x16_bf16 v[2:17], v[224:227], v[246:249], v[2:17]
	s_add_u32 vcc_lo, s6, 0x22a4000
	s_addc_u32 vcc_hi, s7, 0
	s_nop 0
	v_lshl_add_u64 v[174:175], v[182:183], 0, vcc
	global_load_dwordx4 v[174:177], v[174:175], off offset:256
	s_setprio 0
	s_branch .LBB0_281

; __device__ __forceinline__ void lds_barrier() { asm volatile("s_waitcnt lgkmcnt(0)\n\ts_barrier" ::: "memory"); }
; __device__ __forceinline__ f32x16 mfma32(bf16x8 a, bf16x8 b, f32x16 c) { return __builtin_amdgcn_mfma_f32_32x32x16_bf16(a, b, c, 0, 0, 0); }
; __device__ __forceinline__ void gemm_big(const bf16_t* __restrict__ A, long lda, const bf16_t* __restrict__ Bt, int K, f32x16 (&acc)[2][4], unsigned char* lds) {
;     ...
;     for (int kc = 0; kc < nk; ++kc) {
;         bf16x8 af[2][2], bfr[2][4];
;         af[0][0] = *(const bf16x8*)(Ac); af[0][1] = *(const bf16x8*)(Ac + 32 * GLD);
; #pragma unroll
;         for (int ni = 0; ni < 4; ++ni) bfr[0][ni] = *(const bf16x8*)(Bc + ni * 32 * GLD);
;         __builtin_amdgcn_s_setprio(3);
; #pragma unroll
;         for (int ks = 0; ks < 4; ++ks) {
;             const int cb = ks & 1, nb = cb ^ 1;
;             if (ks < 3) {
;                 af[nb][0] = *(const bf16x8*)(Ac + (ks + 1) * 16); af[nb][1] = *(const bf16x8*)(Ac + 32 * GLD + (ks + 1) * 16);
; #pragma unroll
;                 for (int ni = 0; ni < 4; ++ni) bfr[nb][ni] = *(const bf16x8*)(Bc + ni * 32 * GLD + (ks + 1) * 16);
;             }
;             __builtin_amdgcn_sched_barrier(0);
; #pragma unroll
;             for (int ni = 0; ni < 4; ++ni) { acc[0][ni] = mfma32(af[cb][0], bfr[cb][ni], acc[0][ni]); acc[1][ni] = mfma32(af[cb][1], bfr[cb][ni], acc[1][ni]); }
;             __builtin_amdgcn_sched_barrier(0);
;         }
;         __builtin_amdgcn_s_setprio(0);
;         lds_barrier();
;         if (kc + 1 < nk) {
;             lstore();
;             if (kc + 2 < nk) gload(kc + 2);
;             lds_barrier();
;         }
;     }
.LBB0_678:
	s_cmp_gt_u32 s6, 14
	s_cbranch_scc1 .Lmy_gorig_2
	ds_read_b128 v[192:195], v189
	ds_read_b128 v[196:199], v189 offset:4608
	ds_read_b128 v[200:203], v190 offset:18432
	ds_read_b128 v[204:207], v190 offset:23040
	ds_read_b128 v[208:211], v190 offset:27648
	ds_read_b128 v[212:215], v190 offset:32256
	ds_read_b128 v[216:219], v189 offset:32
	ds_read_b128 v[234:237], v189 offset:4640
	ds_read_b128 v[238:241], v190 offset:18464
	ds_read_b128 v[242:245], v190 offset:23072
	ds_read_b128 v[246:249], v190 offset:27680
	ds_read_b128 v[224:227], v190 offset:32288
	s_waitcnt lgkmcnt(9)
	v_mfma_f32_32x32x16_bf16 v[114:129], v[192:195], v[200:203], v[114:129]
	v_mfma_f32_32x32x16_bf16 v[98:113], v[196:199], v[200:203], v[98:113]
	s_waitcnt lgkmcnt(8)
	v_mfma_f32_32x32x16_bf16 v[82:97], v[192:195], v[204:207], v[82:97]
	v_mfma_f32_32x32x16_bf16 v[66:81], v[196:199], v[204:207], v[66:81]
	s_waitcnt lgkmcnt(7)
	v_mfma_f32_32x32x16_bf16 v[50:65], v[192:195], v[208:211], v[50:65]
	v_mfma_f32_32x32x16_bf16 v[34:49], v[196:199], v[208:211], v[34:49]
	s_waitcnt lgkmcnt(6)
	v_mfma_f32_32x32x16_bf16 v[18:33], v[192:195], v[212:215], v[18:33]
	v_mfma_f32_32x32x16_bf16 v[2:17], v[196:199], v[212:215], v[2:17]
	ds_read_b128 v[192:195], v189 offset:64
	ds_read_b128 v[196:199], v189 offset:4672
	ds_read_b128 v[200:203], v190 offset:18496
	ds_read_b128 v[204:207], v190 offset:23104
	ds_read_b128 v[208:211], v190 offset:27712
	ds_read_b128 v[212:215], v190 offset:32320
	s_waitcnt lgkmcnt(9)
	v_mfma_f32_32x32x16_bf16 v[114:129], v[216:219], v[238:241], v[114:129]
	v_mfma_f32_32x32x16_bf16 v[98:113], v[234:237], v[238:241], v[98:113]
	s_waitcnt lgkmcnt(8)
	v_mfma_f32_32x32x16_bf16 v[82:97], v[216:219], v[242:245], v[82:97]
	v_mfma_f32_32x32x16_bf16 v[66:81], v[234:237], v[242:245], v[66:81]
	s_waitcnt lgkmcnt(7)
	v_mfma_f32_32x32x16_bf16 v[50:65], v[216:219], v[246:249], v[50:65]
	v_mfma_f32_32x32x16_bf16 v[34:49], v[234:237], v[246:249], v[34:49]
	s_waitcnt lgkmcnt(6)
	v_mfma_f32_32x32x16_bf16 v[18:33], v[216:219], v[224:227], v[18:33]
	v_mfma_f32_32x32x16_bf16 v[2:17], v[234:237], v[224:227], v[2:17]
	ds_read_b128 v[216:219], v189 offset:96
	ds_read_b128 v[224:227], v189 offset:4704
	ds_read_b128 v[234:237], v190 offset:18528
	ds_read_b128 v[238:241], v190 offset:23136
	ds_read_b128 v[242:245], v190 offset:27744
	ds_read_b128 v[246:249], v190 offset:32352
	s_waitcnt lgkmcnt(9)
	v_mfma_f32_32x32x16_bf16 v[114:129], v[192:195], v[200:203], v[114:129]
	v_mfma_f32_32x32x16_bf16 v[98:113], v[196:199], v[200:203], v[98:113]
	s_waitcnt lgkmcnt(0)
	s_barrier
	s_setprio 3
	s_cmpk_eq_i32 s0, 0x700
	s_cbranch_scc1 .Lmy_gB_2
	v_mfma_f32_32x32x16_bf16 v[82:97], v[192:195], v[204:207], v[82:97]
	s_waitcnt vmcnt(9)
	ds_write_b128 v188, v[130:133]
	v_mfma_f32_32x32x16_bf16 v[66:81], v[196:199], v[204:207], v[66:81]
	ds_write_b128 v188, v[134:137] offset:4608
	v_mfma_f32_32x32x16_bf16 v[50:65], v[192:195], v[208:211], v[50:65]
	ds_write_b128 v188, v[138:141] offset:9216
	s_add_u32 vcc_lo, s0, 0x38a8000
	s_addc_u32 vcc_hi, s1, 0
	s_nop 0
	v_lshl_add_u64 v[130:131], v[184:185], 0, vcc
	global_load_dwordx4 v[130:133], v[130:131], off offset:256
	v_mfma_f32_32x32x16_bf16 v[34:49], v[196:199], v[208:211], v[34:49]
	s_waitcnt vmcnt(8)
	ds_write_b128 v188, v[142:145] offset:13824
	s_add_u32 vcc_lo, s0, 0x38b8000
	s_addc_u32 vcc_hi, s1, 0
	s_nop 0
	v_lshl_add_u64 v[134:135], v[184:185], 0, vcc
	global_load_dwordx4 v[134:137], v[134:135], off offset:256
	v_mfma_f32_32x32x16_bf16 v[18:33], v[192:195], v[212:215], v[18:33]
	ds_write_b128 v188, v[146:149] offset:18432
	s_add_u32 vcc_lo, s0, 0x38c8000
	s_addc_u32 vcc_hi, s1, 0
	s_nop 0
	v_lshl_add_u64 v[138:139], v[184:185], 0, vcc
	global_load_dwordx4 v[138:141], v[138:139], off offset:256
	v_mfma_f32_32x32x16_bf16 v[2:17], v[196:199], v[212:215], v[2:17]
	s_waitcnt vmcnt(9)
	ds_write_b128 v188, v[150:153] offset:23040
	s_add_u32 vcc_lo, s0, 0x38d8000
	s_addc_u32 vcc_hi, s1, 0
	s_nop 0
	v_lshl_add_u64 v[142:143], v[184:185], 0, vcc
	global_load_dwordx4 v[142:145], v[142:143], off offset:256
	v_mfma_f32_32x32x16_bf16 v[114:129], v[216:219], v[234:237], v[114:129]
	s_waitcnt vmcnt(9)
	ds_write_b128 v188, v[154:157] offset:27648
	s_add_u32 vcc_lo, s0, 0x1488000
	s_addc_u32 vcc_hi, s1, 0
	s_nop 0
	v_lshl_add_u64 v[146:147], v[182:183], 0, vcc
	global_load_dwordx4 v[146:149], v[146:147], off offset:256
	v_mfma_f32_32x32x16_bf16 v[98:113], v[224:227], v[234:237], v[98:113]
	s_waitcnt vmcnt(9)
	ds_write_b128 v188, v[158:161] offset:32256
	s_add_u32 vcc_lo, s0, 0x1498000
	s_addc_u32 vcc_hi, s1, 0
	s_nop 0
	v_lshl_add_u64 v[150:151], v[182:183], 0, vcc
	global_load_dwordx4 v[150:153], v[150:151], off offset:256
	v_mfma_f32_32x32x16_bf16 v[82:97], v[216:219], v[238:241], v[82:97]
	s_waitcnt vmcnt(9)
	ds_write_b128 v188, v[162:165] offset:36864
	s_add_u32 vcc_lo, s0, 0x14a8000
	s_addc_u32 vcc_hi, s1, 0
	s_nop 0
	v_lshl_add_u64 v[154:155], v[182:183], 0, vcc
	global_load_dwordx4 v[154:157], v[154:155], off offset:256
	v_mfma_f32_32x32x16_bf16 v[66:81], v[224:227], v[238:241], v[66:81]
	s_waitcnt vmcnt(9)
	ds_write_b128 v188, v[166:169] offset:41472
	s_add_u32 vcc_lo, s0, 0x14b8000
	s_addc_u32 vcc_hi, s1, 0
	s_nop 0
	v_lshl_add_u64 v[158:159], v[182:183], 0, vcc
	global_load_dwordx4 v[158:161], v[158:159], off offset:256
	v_mfma_f32_32x32x16_bf16 v[50:65], v[216:219], v[242:245], v[50:65]
	s_waitcnt vmcnt(9)
	ds_write_b128 v188, v[170:173] offset:46080
	s_add_u32 vcc_lo, s0, 0x14c8000
	s_addc_u32 vcc_hi, s1, 0
	s_nop 0
	v_lshl_add_u64 v[162:163], v[182:183], 0, vcc
	global_load_dwordx4 v[162:165], v[162:163], off offset:256
	v_mfma_f32_32x32x16_bf16 v[34:49], v[224:227], v[242:245], v[34:49]
	s_waitcnt vmcnt(9)
	ds_write_b128 v188, v[174:177] offset:50688
	s_add_u32 vcc_lo, s0, 0x14d8000
	s_addc_u32 vcc_hi, s1, 0
	s_nop 0
	v_lshl_add_u64 v[166:167], v[182:183], 0, vcc
	global_load_dwordx4 v[166:169], v[166:167], off offset:256
	v_mfma_f32_32x32x16_bf16 v[18:33], v[216:219], v[246:249], v[18:33]
	s_add_u32 vcc_lo, s0, 0x14e8000
	s_addc_u32 vcc_hi, s1, 0
	s_nop 0
	v_lshl_add_u64 v[170:171], v[182:183], 0, vcc
	global_load_dwordx4 v[170:173], v[170:171], off offset:256
	v_mfma_f32_32x32x16_bf16 v[2:17], v[224:227], v[246:249], v[2:17]
	s_add_u32 vcc_lo, s0, 0x14f8000
	s_addc_u32 vcc_hi, s1, 0
	s_nop 0
	v_lshl_add_u64 v[174:175], v[182:183], 0, vcc
	global_load_dwordx4 v[174:177], v[174:175], off offset:256
	s_setprio 0
	s_branch .LBB0_676

; __device__ __forceinline__ void lds_barrier() { asm volatile("s_waitcnt lgkmcnt(0)\n\ts_barrier" ::: "memory"); }
; __device__ __forceinline__ f32x16 mfma32(bf16x8 a, bf16x8 b, f32x16 c) { return __builtin_amdgcn_mfma_f32_32x32x16_bf16(a, b, c, 0, 0, 0); }
; __device__ __forceinline__ void gemm_big(const bf16_t* __restrict__ A, long lda, const bf16_t* __restrict__ Bt, int K, f32x16 (&acc)[2][4], unsigned char* lds) {
;     ...
;     for (int kc = 0; kc < nk; ++kc) {
;         bf16x8 af[2][2], bfr[2][4];
;         af[0][0] = *(const bf16x8*)(Ac); af[0][1] = *(const bf16x8*)(Ac + 32 * GLD);
; #pragma unroll
;         for (int ni = 0; ni < 4; ++ni) bfr[0][ni] = *(const bf16x8*)(Bc + ni * 32 * GLD);
;         __builtin_amdgcn_s_setprio(3);
; #pragma unroll
;         for (int ks = 0; ks < 4; ++ks) {
;             const int cb = ks & 1, nb = cb ^ 1;
;             if (ks < 3) {
;                 af[nb][0] = *(const bf16x8*)(Ac + (ks + 1) * 16); af[nb][1] = *(const bf16x8*)(Ac + 32 * GLD + (ks + 1) * 16);
; #pragma unroll
;                 for (int ni = 0; ni < 4; ++ni) bfr[nb][ni] = *(const bf16x8*)(Bc + ni * 32 * GLD + (ks + 1) * 16);
;             }
;             __builtin_amdgcn_sched_barrier(0);
; #pragma unroll
;             for (int ni = 0; ni < 4; ++ni) { acc[0][ni] = mfma32(af[cb][0], bfr[cb][ni], acc[0][ni]); acc[1][ni] = mfma32(af[cb][1], bfr[cb][ni], acc[1][ni]); }
;             __builtin_amdgcn_sched_barrier(0);
;         }
;         __builtin_amdgcn_s_setprio(0);
;         lds_barrier();
;         if (kc + 1 < nk) {
;             lstore();
;             if (kc + 2 < nk) gload(kc + 2);
;             lds_barrier();
;         }
;     }
; __device__ __forceinline__ void phase_resid(const Params& p, const bf16_t* A, long lda, int mrows, const bf16_t* Bt, int K, float* xres, float scale, unsigned char* lds) {
;     ...
;         gemm_big(A + (size_t)pm * 128 * lda, lda, Bt + (size_t)pn * 256 * K, K, acc, lds);
.LBB0_775:
	s_cmp_gt_u32 s14, 42
	s_cbranch_scc1 .Lmy_gorig_1
	ds_read_b128 v[190:193], v187
	ds_read_b128 v[194:197], v187 offset:4608
	ds_read_b128 v[198:201], v188 offset:18432
	ds_read_b128 v[202:205], v188 offset:23040
	ds_read_b128 v[206:209], v188 offset:27648
	ds_read_b128 v[210:213], v188 offset:32256
	ds_read_b128 v[214:217], v187 offset:32
	ds_read_b128 v[218:221], v187 offset:4640
	ds_read_b128 v[234:237], v188 offset:18464
	ds_read_b128 v[238:241], v188 offset:23072
	ds_read_b128 v[242:245], v188 offset:27680
	ds_read_b128 v[246:249], v188 offset:32288
	s_waitcnt lgkmcnt(9)
	v_mfma_f32_32x32x16_bf16 v[114:129], v[190:193], v[198:201], v[114:129]
	v_mfma_f32_32x32x16_bf16 v[50:65], v[194:197], v[198:201], v[50:65]
	s_waitcnt lgkmcnt(8)
	v_mfma_f32_32x32x16_bf16 v[98:113], v[190:193], v[202:205], v[98:113]
	v_mfma_f32_32x32x16_bf16 v[34:49], v[194:197], v[202:205], v[34:49]
	s_waitcnt lgkmcnt(7)
	v_mfma_f32_32x32x16_bf16 v[82:97], v[190:193], v[206:209], v[82:97]
	v_mfma_f32_32x32x16_bf16 v[18:33], v[194:197], v[206:209], v[18:33]
	s_waitcnt lgkmcnt(6)
	v_mfma_f32_32x32x16_bf16 v[66:81], v[190:193], v[210:213], v[66:81]
	v_mfma_f32_32x32x16_bf16 v[2:17], v[194:197], v[210:213], v[2:17]
	ds_read_b128 v[190:193], v187 offset:64
	ds_read_b128 v[194:197], v187 offset:4672
	ds_read_b128 v[198:201], v188 offset:18496
	ds_read_b128 v[202:205], v188 offset:23104
	ds_read_b128 v[206:209], v188 offset:27712
	ds_read_b128 v[210:213], v188 offset:32320
	s_waitcnt lgkmcnt(9)
	v_mfma_f32_32x32x16_bf16 v[114:129], v[214:217], v[234:237], v[114:129]
	v_mfma_f32_32x32x16_bf16 v[50:65], v[218:221], v[234:237], v[50:65]
	s_waitcnt lgkmcnt(8)
	v_mfma_f32_32x32x16_bf16 v[98:113], v[214:217], v[238:241], v[98:113]
	v_mfma_f32_32x32x16_bf16 v[34:49], v[218:221], v[238:241], v[34:49]
	s_waitcnt lgkmcnt(7)
	v_mfma_f32_32x32x16_bf16 v[82:97], v[214:217], v[242:245], v[82:97]
	v_mfma_f32_32x32x16_bf16 v[18:33], v[218:221], v[242:245], v[18:33]
	s_waitcnt lgkmcnt(6)
	v_mfma_f32_32x32x16_bf16 v[66:81], v[214:217], v[246:249], v[66:81]
	v_mfma_f32_32x32x16_bf16 v[2:17], v[218:221], v[246:249], v[2:17]
	ds_read_b128 v[214:217], v187 offset:96
	ds_read_b128 v[218:221], v187 offset:4704
	ds_read_b128 v[234:237], v188 offset:18528
	ds_read_b128 v[238:241], v188 offset:23136
	ds_read_b128 v[242:245], v188 offset:27744
	ds_read_b128 v[246:249], v188 offset:32352
	s_waitcnt lgkmcnt(9)
	v_mfma_f32_32x32x16_bf16 v[114:129], v[190:193], v[198:201], v[114:129]
	v_mfma_f32_32x32x16_bf16 v[50:65], v[194:197], v[198:201], v[50:65]
	s_waitcnt lgkmcnt(0)
	s_barrier
	s_setprio 3
	s_cmpk_eq_i32 s4, 0x1500
	s_cbranch_scc1 .Lmy_gB_1
	v_mfma_f32_32x32x16_bf16 v[98:113], v[190:193], v[202:205], v[98:113]
	s_waitcnt vmcnt(9)
	ds_write_b128 v189, v[130:133]
	v_mfma_f32_32x32x16_bf16 v[34:49], v[194:197], v[202:205], v[34:49]
	ds_write_b128 v189, v[134:137] offset:4608
	v_mfma_f32_32x32x16_bf16 v[82:97], v[190:193], v[206:209], v[82:97]
	ds_write_b128 v189, v[138:141] offset:9216
	s_add_u32 vcc_lo, s4, 0x78a8000
	s_addc_u32 vcc_hi, s5, 0
	s_nop 0
	v_lshl_add_u64 v[130:131], v[184:185], 0, vcc
	global_load_dwordx4 v[130:133], v[130:131], off offset:256
	v_mfma_f32_32x32x16_bf16 v[18:33], v[194:197], v[206:209], v[18:33]
	s_waitcnt vmcnt(8)
	ds_write_b128 v189, v[142:145] offset:13824
	s_add_u32 vcc_lo, s4, 0x78d4000
	s_addc_u32 vcc_hi, s5, 0
	s_nop 0
	v_lshl_add_u64 v[134:135], v[184:185], 0, vcc
	global_load_dwordx4 v[134:137], v[134:135], off offset:256
	v_mfma_f32_32x32x16_bf16 v[66:81], v[190:193], v[210:213], v[66:81]
	ds_write_b128 v189, v[146:149] offset:18432
	s_add_u32 vcc_lo, s4, 0x7900000
	s_addc_u32 vcc_hi, s5, 0
	s_nop 0
	v_lshl_add_u64 v[138:139], v[184:185], 0, vcc
	global_load_dwordx4 v[138:141], v[138:139], off offset:256
	v_mfma_f32_32x32x16_bf16 v[2:17], v[194:197], v[210:213], v[2:17]
	s_waitcnt vmcnt(9)
	ds_write_b128 v189, v[150:153] offset:23040
	s_add_u32 vcc_lo, s4, 0x792c000
	s_addc_u32 vcc_hi, s5, 0
	s_nop 0
	v_lshl_add_u64 v[142:143], v[184:185], 0, vcc
	global_load_dwordx4 v[142:145], v[142:143], off offset:256
	v_mfma_f32_32x32x16_bf16 v[114:129], v[214:217], v[234:237], v[114:129]
	s_waitcnt vmcnt(9)
	ds_write_b128 v189, v[154:157] offset:27648
	s_add_u32 vcc_lo, s4, 0xf08000
	s_addc_u32 vcc_hi, s5, 0
	s_nop 0
	v_lshl_add_u64 v[146:147], v[182:183], 0, vcc
	global_load_dwordx4 v[146:149], v[146:147], off offset:256
	v_mfma_f32_32x32x16_bf16 v[50:65], v[218:221], v[234:237], v[50:65]
	s_waitcnt vmcnt(9)
	ds_write_b128 v189, v[158:161] offset:32256
	s_add_u32 vcc_lo, s4, 0xf34000
	s_addc_u32 vcc_hi, s5, 0
	s_nop 0
	v_lshl_add_u64 v[150:151], v[182:183], 0, vcc
	global_load_dwordx4 v[150:153], v[150:151], off offset:256
	v_mfma_f32_32x32x16_bf16 v[98:113], v[214:217], v[238:241], v[98:113]
	s_waitcnt vmcnt(9)
	ds_write_b128 v189, v[162:165] offset:36864
	s_add_u32 vcc_lo, s4, 0xf60000
	s_addc_u32 vcc_hi, s5, 0
	s_nop 0
	v_lshl_add_u64 v[154:155], v[182:183], 0, vcc
	global_load_dwordx4 v[154:157], v[154:155], off offset:256
	v_mfma_f32_32x32x16_bf16 v[34:49], v[218:221], v[238:241], v[34:49]
	s_waitcnt vmcnt(9)
	ds_write_b128 v189, v[166:169] offset:41472
	s_add_u32 vcc_lo, s4, 0xf8c000
	s_addc_u32 vcc_hi, s5, 0
	s_nop 0
	v_lshl_add_u64 v[158:159], v[182:183], 0, vcc
	global_load_dwordx4 v[158:161], v[158:159], off offset:256
	v_mfma_f32_32x32x16_bf16 v[82:97], v[214:217], v[242:245], v[82:97]
	s_waitcnt vmcnt(9)
	ds_write_b128 v189, v[170:173] offset:46080
	s_add_u32 vcc_lo, s4, 0xfb8000
	s_addc_u32 vcc_hi, s5, 0
	s_nop 0
	v_lshl_add_u64 v[162:163], v[182:183], 0, vcc
	global_load_dwordx4 v[162:165], v[162:163], off offset:256
	v_mfma_f32_32x32x16_bf16 v[18:33], v[218:221], v[242:245], v[18:33]
	s_waitcnt vmcnt(9)
	ds_write_b128 v189, v[174:177] offset:50688
	s_add_u32 vcc_lo, s4, 0xfe4000
	s_addc_u32 vcc_hi, s5, 0
	s_nop 0
	v_lshl_add_u64 v[166:167], v[182:183], 0, vcc
	global_load_dwordx4 v[166:169], v[166:167], off offset:256
	v_mfma_f32_32x32x16_bf16 v[66:81], v[214:217], v[246:249], v[66:81]
	s_add_u32 vcc_lo, s4, 0x1010000
	s_addc_u32 vcc_hi, s5, 0
	s_nop 0
	v_lshl_add_u64 v[170:171], v[182:183], 0, vcc
	global_load_dwordx4 v[170:173], v[170:171], off offset:256
	v_mfma_f32_32x32x16_bf16 v[2:17], v[218:221], v[246:249], v[2:17]
	s_add_u32 vcc_lo, s4, 0x103c000
	s_addc_u32 vcc_hi, s5, 0
	s_nop 0
	v_lshl_add_u64 v[174:175], v[182:183], 0, vcc
	global_load_dwordx4 v[174:177], v[174:175], off offset:256
	s_setprio 0
	s_branch .LBB0_773

; __device__ __forceinline__ void lds_barrier() { asm volatile("s_waitcnt lgkmcnt(0)\n\ts_barrier" ::: "memory"); }
; __device__ __forceinline__ f32x16 mfma32(bf16x8 a, bf16x8 b, f32x16 c) { return __builtin_amdgcn_mfma_f32_32x32x16_bf16(a, b, c, 0, 0, 0); }
; __device__ __forceinline__ void gemm_big(const bf16_t* __restrict__ A, long lda, const bf16_t* __restrict__ Bt, int K, f32x16 (&acc)[2][4], unsigned char* lds) {
;     ...
;     for (int kc = 0; kc < nk; ++kc) {
;         bf16x8 af[2][2], bfr[2][4];
;         af[0][0] = *(const bf16x8*)(Ac); af[0][1] = *(const bf16x8*)(Ac + 32 * GLD);
; #pragma unroll
;         for (int ni = 0; ni < 4; ++ni) bfr[0][ni] = *(const bf16x8*)(Bc + ni * 32 * GLD);
;         __builtin_amdgcn_s_setprio(3);
; #pragma unroll
;         for (int ks = 0; ks < 4; ++ks) {
;             const int cb = ks & 1, nb = cb ^ 1;
;             if (ks < 3) {
;                 af[nb][0] = *(const bf16x8*)(Ac + (ks + 1) * 16); af[nb][1] = *(const bf16x8*)(Ac + 32 * GLD + (ks + 1) * 16);
; #pragma unroll
;                 for (int ni = 0; ni < 4; ++ni) bfr[nb][ni] = *(const bf16x8*)(Bc + ni * 32 * GLD + (ks + 1) * 16);
;             }
;             __builtin_amdgcn_sched_barrier(0);
; #pragma unroll
;             for (int ni = 0; ni < 4; ++ni) { acc[0][ni] = mfma32(af[cb][0], bfr[cb][ni], acc[0][ni]); acc[1][ni] = mfma32(af[cb][1], bfr[cb][ni], acc[1][ni]); }
;             __builtin_amdgcn_sched_barrier(0);
;         }
;         __builtin_amdgcn_s_setprio(0);
;         lds_barrier();
;         if (kc + 1 < nk) {
;             lstore();
;             if (kc + 2 < nk) gload(kc + 2);
;             lds_barrier();
;         }
;     }
.LBB0_788:
	s_cmp_gt_u32 s5, 14
	s_cbranch_scc1 .Lmy_gorig_0
	ds_read_b128 v[190:193], v188
	ds_read_b128 v[194:197], v188 offset:4608
	ds_read_b128 v[198:201], v189 offset:18432
	ds_read_b128 v[202:205], v189 offset:23040
	ds_read_b128 v[206:209], v189 offset:27648
	ds_read_b128 v[210:213], v189 offset:32256
	ds_read_b128 v[214:217], v188 offset:32
	ds_read_b128 v[234:237], v188 offset:4640
	ds_read_b128 v[238:241], v189 offset:18464
	ds_read_b128 v[242:245], v189 offset:23072
	ds_read_b128 v[246:249], v189 offset:27680
	ds_read_b128 v[218:221], v189 offset:32288
	s_waitcnt lgkmcnt(9)
	v_mfma_f32_32x32x16_bf16 v[114:129], v[190:193], v[198:201], v[114:129]
	v_mfma_f32_32x32x16_bf16 v[82:97], v[194:197], v[198:201], v[82:97]
	s_waitcnt lgkmcnt(8)
	v_mfma_f32_32x32x16_bf16 v[98:113], v[190:193], v[202:205], v[98:113]
	v_mfma_f32_32x32x16_bf16 v[66:81], v[194:197], v[202:205], v[66:81]
	s_waitcnt lgkmcnt(7)
	v_mfma_f32_32x32x16_bf16 v[50:65], v[190:193], v[206:209], v[50:65]
	v_mfma_f32_32x32x16_bf16 v[18:33], v[194:197], v[206:209], v[18:33]
	s_waitcnt lgkmcnt(6)
	v_mfma_f32_32x32x16_bf16 v[34:49], v[190:193], v[210:213], v[34:49]
	v_mfma_f32_32x32x16_bf16 v[2:17], v[194:197], v[210:213], v[2:17]
	ds_read_b128 v[190:193], v188 offset:64
	ds_read_b128 v[194:197], v188 offset:4672
	ds_read_b128 v[198:201], v189 offset:18496
	ds_read_b128 v[202:205], v189 offset:23104
	ds_read_b128 v[206:209], v189 offset:27712
	ds_read_b128 v[210:213], v189 offset:32320
	s_waitcnt lgkmcnt(9)
	v_mfma_f32_32x32x16_bf16 v[114:129], v[214:217], v[238:241], v[114:129]
	v_mfma_f32_32x32x16_bf16 v[82:97], v[234:237], v[238:241], v[82:97]
	s_waitcnt lgkmcnt(8)
	v_mfma_f32_32x32x16_bf16 v[98:113], v[214:217], v[242:245], v[98:113]
	v_mfma_f32_32x32x16_bf16 v[66:81], v[234:237], v[242:245], v[66:81]
	s_waitcnt lgkmcnt(7)
	v_mfma_f32_32x32x16_bf16 v[50:65], v[214:217], v[246:249], v[50:65]
	v_mfma_f32_32x32x16_bf16 v[18:33], v[234:237], v[246:249], v[18:33]
	s_waitcnt lgkmcnt(6)
	v_mfma_f32_32x32x16_bf16 v[34:49], v[214:217], v[218:221], v[34:49]
	v_mfma_f32_32x32x16_bf16 v[2:17], v[234:237], v[218:221], v[2:17]
	ds_read_b128 v[214:217], v188 offset:96
	ds_read_b128 v[218:221], v188 offset:4704
	ds_read_b128 v[234:237], v189 offset:18528
	ds_read_b128 v[238:241], v189 offset:23136
	ds_read_b128 v[242:245], v189 offset:27744
	ds_read_b128 v[246:249], v189 offset:32352
	s_waitcnt lgkmcnt(9)
	v_mfma_f32_32x32x16_bf16 v[114:129], v[190:193], v[198:201], v[114:129]
	v_mfma_f32_32x32x16_bf16 v[82:97], v[194:197], v[198:201], v[82:97]
	s_waitcnt lgkmcnt(0)
	s_barrier
	s_setprio 3
	s_cmpk_eq_i32 s6, 0x700
	s_cbranch_scc1 .Lmy_gB_0
	v_mfma_f32_32x32x16_bf16 v[98:113], v[190:193], v[202:205], v[98:113]
	s_waitcnt vmcnt(9)
	ds_write_b128 v187, v[130:133]
	v_mfma_f32_32x32x16_bf16 v[66:81], v[194:197], v[202:205], v[66:81]
	ds_write_b128 v187, v[134:137] offset:4608
	v_mfma_f32_32x32x16_bf16 v[50:65], v[190:193], v[206:209], v[50:65]
	ds_write_b128 v187, v[138:141] offset:9216
	s_add_u32 vcc_lo, s6, 0x38a8000
	s_addc_u32 vcc_hi, s7, 0
	s_nop 0
	v_lshl_add_u64 v[130:131], v[184:185], 0, vcc
	global_load_dwordx4 v[130:133], v[130:131], off offset:256
	v_mfma_f32_32x32x16_bf16 v[18:33], v[194:197], v[206:209], v[18:33]
	s_waitcnt vmcnt(8)
	ds_write_b128 v187, v[142:145] offset:13824
	s_add_u32 vcc_lo, s6, 0x38b8000
	s_addc_u32 vcc_hi, s7, 0
	s_nop 0
	v_lshl_add_u64 v[134:135], v[184:185], 0, vcc
	global_load_dwordx4 v[134:137], v[134:135], off offset:256
	v_mfma_f32_32x32x16_bf16 v[34:49], v[190:193], v[210:213], v[34:49]
	ds_write_b128 v187, v[146:149] offset:18432
	s_add_u32 vcc_lo, s6, 0x38c8000
	s_addc_u32 vcc_hi, s7, 0
	s_nop 0
	v_lshl_add_u64 v[138:139], v[184:185], 0, vcc
	global_load_dwordx4 v[138:141], v[138:139], off offset:256
	v_mfma_f32_32x32x16_bf16 v[2:17], v[194:197], v[210:213], v[2:17]
	s_waitcnt vmcnt(9)
	ds_write_b128 v187, v[150:153] offset:23040
	s_add_u32 vcc_lo, s6, 0x38d8000
	s_addc_u32 vcc_hi, s7, 0
	s_nop 0
	v_lshl_add_u64 v[142:143], v[184:185], 0, vcc
	global_load_dwordx4 v[142:145], v[142:143], off offset:256
	v_mfma_f32_32x32x16_bf16 v[114:129], v[214:217], v[234:237], v[114:129]
	s_waitcnt vmcnt(9)
	ds_write_b128 v187, v[154:157] offset:27648
	s_add_u32 vcc_lo, s6, 0x408000
	s_addc_u32 vcc_hi, s7, 0
	s_nop 0
	v_lshl_add_u64 v[146:147], v[182:183], 0, vcc
	global_load_dwordx4 v[146:149], v[146:147], off offset:256
	v_mfma_f32_32x32x16_bf16 v[82:97], v[218:221], v[234:237], v[82:97]
	s_waitcnt vmcnt(9)
	ds_write_b128 v187, v[158:161] offset:32256
	s_add_u32 vcc_lo, s6, 0x418000
	s_addc_u32 vcc_hi, s7, 0
	s_nop 0
	v_lshl_add_u64 v[150:151], v[182:183], 0, vcc
	global_load_dwordx4 v[150:153], v[150:151], off offset:256
	v_mfma_f32_32x32x16_bf16 v[98:113], v[214:217], v[238:241], v[98:113]
	s_waitcnt vmcnt(9)
	ds_write_b128 v187, v[162:165] offset:36864
	s_add_u32 vcc_lo, s6, 0x428000
	s_addc_u32 vcc_hi, s7, 0
	s_nop 0
	v_lshl_add_u64 v[154:155], v[182:183], 0, vcc
	global_load_dwordx4 v[154:157], v[154:155], off offset:256
	v_mfma_f32_32x32x16_bf16 v[66:81], v[218:221], v[238:241], v[66:81]
	s_waitcnt vmcnt(9)
	ds_write_b128 v187, v[166:169] offset:41472
	s_add_u32 vcc_lo, s6, 0x438000
	s_addc_u32 vcc_hi, s7, 0
	s_nop 0
	v_lshl_add_u64 v[158:159], v[182:183], 0, vcc
	global_load_dwordx4 v[158:161], v[158:159], off offset:256
	v_mfma_f32_32x32x16_bf16 v[50:65], v[214:217], v[242:245], v[50:65]
	s_waitcnt vmcnt(9)
	ds_write_b128 v187, v[170:173] offset:46080
	s_add_u32 vcc_lo, s6, 0x448000
	s_addc_u32 vcc_hi, s7, 0
	s_nop 0
	v_lshl_add_u64 v[162:163], v[182:183], 0, vcc
	global_load_dwordx4 v[162:165], v[162:163], off offset:256
	v_mfma_f32_32x32x16_bf16 v[18:33], v[218:221], v[242:245], v[18:33]
	s_waitcnt vmcnt(9)
	ds_write_b128 v187, v[174:177] offset:50688
	s_add_u32 vcc_lo, s6, 0x458000
	s_addc_u32 vcc_hi, s7, 0
	s_nop 0
	v_lshl_add_u64 v[166:167], v[182:183], 0, vcc
	global_load_dwordx4 v[166:169], v[166:167], off offset:256
	v_mfma_f32_32x32x16_bf16 v[34:49], v[214:217], v[246:249], v[34:49]
	s_add_u32 vcc_lo, s6, 0x468000
	s_addc_u32 vcc_hi, s7, 0
	s_nop 0
	v_lshl_add_u64 v[170:171], v[182:183], 0, vcc
	global_load_dwordx4 v[170:173], v[170:171], off offset:256
	v_mfma_f32_32x32x16_bf16 v[2:17], v[218:221], v[246:249], v[2:17]
	s_add_u32 vcc_lo, s6, 0x478000
	s_addc_u32 vcc_hi, s7, 0
	s_nop 0
	v_lshl_add_u64 v[174:175], v[182:183], 0, vcc
	global_load_dwordx4 v[174:177], v[174:175], off offset:256
	s_setprio 0
	s_branch .LBB0_786
